# ph0 mod-GEMV inner loops rewritten by hand: 8 row loads in flight instead of 1 (same FMA order), on top of v35
# speedup vs baseline: 1.0210x; 1.0035x over previous
.LBB0_117:
	s_mov_b32 s73, 0
	s_mov_b32 s74, 0x20000
	s_mov_b32 s75, 0
	v_mov_b64_e32 v[228:229], v[88:89]
	s_mov_b32 s72, 0x4000
	v_lshl_add_u64 v[230:231], v[88:89], 0, s[72:73]
	s_mov_b32 s72, 0x8000
	v_lshl_add_u64 v[232:233], v[88:89], 0, s[72:73]
	s_mov_b32 s72, 0xc000
	v_lshl_add_u64 v[234:235], v[88:89], 0, s[72:73]
	s_mov_b32 s72, 0x10000
	v_lshl_add_u64 v[236:237], v[88:89], 0, s[72:73]
	s_mov_b32 s72, 0x14000
	v_lshl_add_u64 v[238:239], v[88:89], 0, s[72:73]
	s_mov_b32 s72, 0x18000
	v_lshl_add_u64 v[240:241], v[88:89], 0, s[72:73]
	s_mov_b32 s72, 0x1c000
	v_lshl_add_u64 v[242:243], v[88:89], 0, s[72:73]
	global_load_dwordx4 v[164:167], v[228:229], off
	v_lshl_add_u64 v[228:229], v[228:229], 0, s[74:75]
	global_load_dwordx4 v[168:171], v[230:231], off
	v_lshl_add_u64 v[230:231], v[230:231], 0, s[74:75]
	global_load_dwordx4 v[172:175], v[232:233], off
	v_lshl_add_u64 v[232:233], v[232:233], 0, s[74:75]
	global_load_dwordx4 v[176:179], v[234:235], off
	v_lshl_add_u64 v[234:235], v[234:235], 0, s[74:75]
	global_load_dwordx4 v[180:183], v[236:237], off
	v_lshl_add_u64 v[236:237], v[236:237], 0, s[74:75]
	global_load_dwordx4 v[184:187], v[238:239], off
	v_lshl_add_u64 v[238:239], v[238:239], 0, s[74:75]
	global_load_dwordx4 v[188:191], v[240:241], off
	v_lshl_add_u64 v[240:241], v[240:241], 0, s[74:75]
	global_load_dwordx4 v[192:195], v[242:243], off
	v_lshl_add_u64 v[242:243], v[242:243], 0, s[74:75]
	s_mov_b32 s76, 31
.Lgemv_kv_loop:
	v_mov_b32_e32 v244, s2
	ds_read_b128 v[196:199], v244
	ds_read_b128 v[200:203], v244 offset:16
	ds_read_b128 v[204:207], v244 offset:1024
	ds_read_b128 v[208:211], v244 offset:1040
	ds_read_b128 v[212:215], v244 offset:2048
	ds_read_b128 v[216:219], v244 offset:2064
	ds_read_b128 v[220:223], v244 offset:3072
	ds_read_b128 v[224:227], v244 offset:3088
	s_add_i32 s2, s2, 32
	s_waitcnt lgkmcnt(0)
	s_waitcnt vmcnt(7)
	v_pk_fma_f32 v[8:9], v[164:165], v[196:197], v[8:9] op_sel_hi:[1,0,1]
	v_pk_fma_f32 v[10:11], v[166:167], v[196:197], v[10:11] op_sel_hi:[1,0,1]
	v_pk_fma_f32 v[12:13], v[164:165], v[204:205], v[12:13] op_sel_hi:[1,0,1]
	v_pk_fma_f32 v[14:15], v[166:167], v[204:205], v[14:15] op_sel_hi:[1,0,1]
	v_pk_fma_f32 v[4:5], v[164:165], v[212:213], v[4:5] op_sel_hi:[1,0,1]
	v_pk_fma_f32 v[6:7], v[166:167], v[212:213], v[6:7] op_sel_hi:[1,0,1]
	v_pk_fma_f32 v[0:1], v[164:165], v[220:221], v[0:1] op_sel_hi:[1,0,1]
	v_pk_fma_f32 v[2:3], v[166:167], v[220:221], v[2:3] op_sel_hi:[1,0,1]
	global_load_dwordx4 v[164:167], v[228:229], off
	v_lshl_add_u64 v[228:229], v[228:229], 0, s[74:75]
	s_waitcnt vmcnt(7)
	v_pk_fma_f32 v[8:9], v[168:169], v[196:197], v[8:9] op_sel:[0,1,0]
	v_pk_fma_f32 v[10:11], v[170:171], v[196:197], v[10:11] op_sel:[0,1,0]
	v_pk_fma_f32 v[12:13], v[168:169], v[204:205], v[12:13] op_sel:[0,1,0]
	v_pk_fma_f32 v[14:15], v[170:171], v[204:205], v[14:15] op_sel:[0,1,0]
	v_pk_fma_f32 v[4:5], v[168:169], v[212:213], v[4:5] op_sel:[0,1,0]
	v_pk_fma_f32 v[6:7], v[170:171], v[212:213], v[6:7] op_sel:[0,1,0]
	v_pk_fma_f32 v[0:1], v[168:169], v[220:221], v[0:1] op_sel:[0,1,0]
	v_pk_fma_f32 v[2:3], v[170:171], v[220:221], v[2:3] op_sel:[0,1,0]
	global_load_dwordx4 v[168:171], v[230:231], off
	v_lshl_add_u64 v[230:231], v[230:231], 0, s[74:75]
	s_waitcnt vmcnt(7)
	v_pk_fma_f32 v[8:9], v[172:173], v[198:199], v[8:9] op_sel_hi:[1,0,1]
	v_pk_fma_f32 v[10:11], v[174:175], v[198:199], v[10:11] op_sel_hi:[1,0,1]
	v_pk_fma_f32 v[12:13], v[172:173], v[206:207], v[12:13] op_sel_hi:[1,0,1]
	v_pk_fma_f32 v[14:15], v[174:175], v[206:207], v[14:15] op_sel_hi:[1,0,1]
	v_pk_fma_f32 v[4:5], v[172:173], v[214:215], v[4:5] op_sel_hi:[1,0,1]
	v_pk_fma_f32 v[6:7], v[174:175], v[214:215], v[6:7] op_sel_hi:[1,0,1]
	v_pk_fma_f32 v[0:1], v[172:173], v[222:223], v[0:1] op_sel_hi:[1,0,1]
	v_pk_fma_f32 v[2:3], v[174:175], v[222:223], v[2:3] op_sel_hi:[1,0,1]
	global_load_dwordx4 v[172:175], v[232:233], off
	v_lshl_add_u64 v[232:233], v[232:233], 0, s[74:75]
	s_waitcnt vmcnt(7)
	v_pk_fma_f32 v[8:9], v[176:177], v[198:199], v[8:9] op_sel:[0,1,0]
	v_pk_fma_f32 v[10:11], v[178:179], v[198:199], v[10:11] op_sel:[0,1,0]
	v_pk_fma_f32 v[12:13], v[176:177], v[206:207], v[12:13] op_sel:[0,1,0]
	v_pk_fma_f32 v[14:15], v[178:179], v[206:207], v[14:15] op_sel:[0,1,0]
	v_pk_fma_f32 v[4:5], v[176:177], v[214:215], v[4:5] op_sel:[0,1,0]
	v_pk_fma_f32 v[6:7], v[178:179], v[214:215], v[6:7] op_sel:[0,1,0]
	v_pk_fma_f32 v[0:1], v[176:177], v[222:223], v[0:1] op_sel:[0,1,0]
	v_pk_fma_f32 v[2:3], v[178:179], v[222:223], v[2:3] op_sel:[0,1,0]
	global_load_dwordx4 v[176:179], v[234:235], off
	v_lshl_add_u64 v[234:235], v[234:235], 0, s[74:75]
	s_waitcnt vmcnt(7)
	v_pk_fma_f32 v[8:9], v[180:181], v[200:201], v[8:9] op_sel_hi:[1,0,1]
	v_pk_fma_f32 v[10:11], v[182:183], v[200:201], v[10:11] op_sel_hi:[1,0,1]
	v_pk_fma_f32 v[12:13], v[180:181], v[208:209], v[12:13] op_sel_hi:[1,0,1]
	v_pk_fma_f32 v[14:15], v[182:183], v[208:209], v[14:15] op_sel_hi:[1,0,1]
	v_pk_fma_f32 v[4:5], v[180:181], v[216:217], v[4:5] op_sel_hi:[1,0,1]
	v_pk_fma_f32 v[6:7], v[182:183], v[216:217], v[6:7] op_sel_hi:[1,0,1]
	v_pk_fma_f32 v[0:1], v[180:181], v[224:225], v[0:1] op_sel_hi:[1,0,1]
	v_pk_fma_f32 v[2:3], v[182:183], v[224:225], v[2:3] op_sel_hi:[1,0,1]
	global_load_dwordx4 v[180:183], v[236:237], off
	v_lshl_add_u64 v[236:237], v[236:237], 0, s[74:75]
	s_waitcnt vmcnt(7)
	v_pk_fma_f32 v[8:9], v[184:185], v[200:201], v[8:9] op_sel:[0,1,0]
	v_pk_fma_f32 v[10:11], v[186:187], v[200:201], v[10:11] op_sel:[0,1,0]
	v_pk_fma_f32 v[12:13], v[184:185], v[208:209], v[12:13] op_sel:[0,1,0]
	v_pk_fma_f32 v[14:15], v[186:187], v[208:209], v[14:15] op_sel:[0,1,0]
	v_pk_fma_f32 v[4:5], v[184:185], v[216:217], v[4:5] op_sel:[0,1,0]
	v_pk_fma_f32 v[6:7], v[186:187], v[216:217], v[6:7] op_sel:[0,1,0]
	v_pk_fma_f32 v[0:1], v[184:185], v[224:225], v[0:1] op_sel:[0,1,0]
	v_pk_fma_f32 v[2:3], v[186:187], v[224:225], v[2:3] op_sel:[0,1,0]
	global_load_dwordx4 v[184:187], v[238:239], off
	v_lshl_add_u64 v[238:239], v[238:239], 0, s[74:75]
	s_waitcnt vmcnt(7)
	v_pk_fma_f32 v[8:9], v[188:189], v[202:203], v[8:9] op_sel_hi:[1,0,1]
	v_pk_fma_f32 v[10:11], v[190:191], v[202:203], v[10:11] op_sel_hi:[1,0,1]
	v_pk_fma_f32 v[12:13], v[188:189], v[210:211], v[12:13] op_sel_hi:[1,0,1]
	v_pk_fma_f32 v[14:15], v[190:191], v[210:211], v[14:15] op_sel_hi:[1,0,1]
	v_pk_fma_f32 v[4:5], v[188:189], v[218:219], v[4:5] op_sel_hi:[1,0,1]
	v_pk_fma_f32 v[6:7], v[190:191], v[218:219], v[6:7] op_sel_hi:[1,0,1]
	v_pk_fma_f32 v[0:1], v[188:189], v[226:227], v[0:1] op_sel_hi:[1,0,1]
	v_pk_fma_f32 v[2:3], v[190:191], v[226:227], v[2:3] op_sel_hi:[1,0,1]
	global_load_dwordx4 v[188:191], v[240:241], off
	v_lshl_add_u64 v[240:241], v[240:241], 0, s[74:75]
	s_waitcnt vmcnt(7)
	v_pk_fma_f32 v[8:9], v[192:193], v[202:203], v[8:9] op_sel:[0,1,0]
	v_pk_fma_f32 v[10:11], v[194:195], v[202:203], v[10:11] op_sel:[0,1,0]
	v_pk_fma_f32 v[12:13], v[192:193], v[210:211], v[12:13] op_sel:[0,1,0]
	v_pk_fma_f32 v[14:15], v[194:195], v[210:211], v[14:15] op_sel:[0,1,0]
	v_pk_fma_f32 v[4:5], v[192:193], v[218:219], v[4:5] op_sel:[0,1,0]
	v_pk_fma_f32 v[6:7], v[194:195], v[218:219], v[6:7] op_sel:[0,1,0]
	v_pk_fma_f32 v[0:1], v[192:193], v[226:227], v[0:1] op_sel:[0,1,0]
	v_pk_fma_f32 v[2:3], v[194:195], v[226:227], v[2:3] op_sel:[0,1,0]
	global_load_dwordx4 v[192:195], v[242:243], off
	v_lshl_add_u64 v[242:243], v[242:243], 0, s[74:75]
	s_add_i32 s76, s76, -1
	s_cmp_eq_u32 s76, 0
	s_cbranch_scc0 .Lgemv_kv_loop
	v_mov_b32_e32 v244, s2
	ds_read_b128 v[196:199], v244
	ds_read_b128 v[200:203], v244 offset:16
	ds_read_b128 v[204:207], v244 offset:1024
	ds_read_b128 v[208:211], v244 offset:1040
	ds_read_b128 v[212:215], v244 offset:2048
	ds_read_b128 v[216:219], v244 offset:2064
	ds_read_b128 v[220:223], v244 offset:3072
	ds_read_b128 v[224:227], v244 offset:3088
	s_waitcnt lgkmcnt(0)
	s_waitcnt vmcnt(7)
	v_pk_fma_f32 v[8:9], v[164:165], v[196:197], v[8:9] op_sel_hi:[1,0,1]
	v_pk_fma_f32 v[10:11], v[166:167], v[196:197], v[10:11] op_sel_hi:[1,0,1]
	v_pk_fma_f32 v[12:13], v[164:165], v[204:205], v[12:13] op_sel_hi:[1,0,1]
	v_pk_fma_f32 v[14:15], v[166:167], v[204:205], v[14:15] op_sel_hi:[1,0,1]
	v_pk_fma_f32 v[4:5], v[164:165], v[212:213], v[4:5] op_sel_hi:[1,0,1]
	v_pk_fma_f32 v[6:7], v[166:167], v[212:213], v[6:7] op_sel_hi:[1,0,1]
	v_pk_fma_f32 v[0:1], v[164:165], v[220:221], v[0:1] op_sel_hi:[1,0,1]
	v_pk_fma_f32 v[2:3], v[166:167], v[220:221], v[2:3] op_sel_hi:[1,0,1]
	s_waitcnt vmcnt(6)
	v_pk_fma_f32 v[8:9], v[168:169], v[196:197], v[8:9] op_sel:[0,1,0]
	v_pk_fma_f32 v[10:11], v[170:171], v[196:197], v[10:11] op_sel:[0,1,0]
	v_pk_fma_f32 v[12:13], v[168:169], v[204:205], v[12:13] op_sel:[0,1,0]
	v_pk_fma_f32 v[14:15], v[170:171], v[204:205], v[14:15] op_sel:[0,1,0]
	v_pk_fma_f32 v[4:5], v[168:169], v[212:213], v[4:5] op_sel:[0,1,0]
	v_pk_fma_f32 v[6:7], v[170:171], v[212:213], v[6:7] op_sel:[0,1,0]
	v_pk_fma_f32 v[0:1], v[168:169], v[220:221], v[0:1] op_sel:[0,1,0]
	v_pk_fma_f32 v[2:3], v[170:171], v[220:221], v[2:3] op_sel:[0,1,0]
	s_waitcnt vmcnt(5)
	v_pk_fma_f32 v[8:9], v[172:173], v[198:199], v[8:9] op_sel_hi:[1,0,1]
	v_pk_fma_f32 v[10:11], v[174:175], v[198:199], v[10:11] op_sel_hi:[1,0,1]
	v_pk_fma_f32 v[12:13], v[172:173], v[206:207], v[12:13] op_sel_hi:[1,0,1]
	v_pk_fma_f32 v[14:15], v[174:175], v[206:207], v[14:15] op_sel_hi:[1,0,1]
	v_pk_fma_f32 v[4:5], v[172:173], v[214:215], v[4:5] op_sel_hi:[1,0,1]
	v_pk_fma_f32 v[6:7], v[174:175], v[214:215], v[6:7] op_sel_hi:[1,0,1]
	v_pk_fma_f32 v[0:1], v[172:173], v[222:223], v[0:1] op_sel_hi:[1,0,1]
	v_pk_fma_f32 v[2:3], v[174:175], v[222:223], v[2:3] op_sel_hi:[1,0,1]
	s_waitcnt vmcnt(4)
	v_pk_fma_f32 v[8:9], v[176:177], v[198:199], v[8:9] op_sel:[0,1,0]
	v_pk_fma_f32 v[10:11], v[178:179], v[198:199], v[10:11] op_sel:[0,1,0]
	v_pk_fma_f32 v[12:13], v[176:177], v[206:207], v[12:13] op_sel:[0,1,0]
	v_pk_fma_f32 v[14:15], v[178:179], v[206:207], v[14:15] op_sel:[0,1,0]
	v_pk_fma_f32 v[4:5], v[176:177], v[214:215], v[4:5] op_sel:[0,1,0]
	v_pk_fma_f32 v[6:7], v[178:179], v[214:215], v[6:7] op_sel:[0,1,0]
	v_pk_fma_f32 v[0:1], v[176:177], v[222:223], v[0:1] op_sel:[0,1,0]
	v_pk_fma_f32 v[2:3], v[178:179], v[222:223], v[2:3] op_sel:[0,1,0]
	s_waitcnt vmcnt(3)
	v_pk_fma_f32 v[8:9], v[180:181], v[200:201], v[8:9] op_sel_hi:[1,0,1]
	v_pk_fma_f32 v[10:11], v[182:183], v[200:201], v[10:11] op_sel_hi:[1,0,1]
	v_pk_fma_f32 v[12:13], v[180:181], v[208:209], v[12:13] op_sel_hi:[1,0,1]
	v_pk_fma_f32 v[14:15], v[182:183], v[208:209], v[14:15] op_sel_hi:[1,0,1]
	v_pk_fma_f32 v[4:5], v[180:181], v[216:217], v[4:5] op_sel_hi:[1,0,1]
	v_pk_fma_f32 v[6:7], v[182:183], v[216:217], v[6:7] op_sel_hi:[1,0,1]
	v_pk_fma_f32 v[0:1], v[180:181], v[224:225], v[0:1] op_sel_hi:[1,0,1]
	v_pk_fma_f32 v[2:3], v[182:183], v[224:225], v[2:3] op_sel_hi:[1,0,1]
	s_waitcnt vmcnt(2)
	v_pk_fma_f32 v[8:9], v[184:185], v[200:201], v[8:9] op_sel:[0,1,0]
	v_pk_fma_f32 v[10:11], v[186:187], v[200:201], v[10:11] op_sel:[0,1,0]
	v_pk_fma_f32 v[12:13], v[184:185], v[208:209], v[12:13] op_sel:[0,1,0]
	v_pk_fma_f32 v[14:15], v[186:187], v[208:209], v[14:15] op_sel:[0,1,0]
	v_pk_fma_f32 v[4:5], v[184:185], v[216:217], v[4:5] op_sel:[0,1,0]
	v_pk_fma_f32 v[6:7], v[186:187], v[216:217], v[6:7] op_sel:[0,1,0]
	v_pk_fma_f32 v[0:1], v[184:185], v[224:225], v[0:1] op_sel:[0,1,0]
	v_pk_fma_f32 v[2:3], v[186:187], v[224:225], v[2:3] op_sel:[0,1,0]
	s_waitcnt vmcnt(1)
	v_pk_fma_f32 v[8:9], v[188:189], v[202:203], v[8:9] op_sel_hi:[1,0,1]
	v_pk_fma_f32 v[10:11], v[190:191], v[202:203], v[10:11] op_sel_hi:[1,0,1]
	v_pk_fma_f32 v[12:13], v[188:189], v[210:211], v[12:13] op_sel_hi:[1,0,1]
	v_pk_fma_f32 v[14:15], v[190:191], v[210:211], v[14:15] op_sel_hi:[1,0,1]
	v_pk_fma_f32 v[4:5], v[188:189], v[218:219], v[4:5] op_sel_hi:[1,0,1]
	v_pk_fma_f32 v[6:7], v[190:191], v[218:219], v[6:7] op_sel_hi:[1,0,1]
	v_pk_fma_f32 v[0:1], v[188:189], v[226:227], v[0:1] op_sel_hi:[1,0,1]
	v_pk_fma_f32 v[2:3], v[190:191], v[226:227], v[2:3] op_sel_hi:[1,0,1]
	s_waitcnt vmcnt(0)
	v_pk_fma_f32 v[8:9], v[192:193], v[202:203], v[8:9] op_sel:[0,1,0]
	v_pk_fma_f32 v[10:11], v[194:195], v[202:203], v[10:11] op_sel:[0,1,0]
	v_pk_fma_f32 v[12:13], v[192:193], v[210:211], v[12:13] op_sel:[0,1,0]
	v_pk_fma_f32 v[14:15], v[194:195], v[210:211], v[14:15] op_sel:[0,1,0]
	v_pk_fma_f32 v[4:5], v[192:193], v[218:219], v[4:5] op_sel:[0,1,0]
	v_pk_fma_f32 v[6:7], v[194:195], v[218:219], v[6:7] op_sel:[0,1,0]
	v_pk_fma_f32 v[0:1], v[192:193], v[226:227], v[0:1] op_sel:[0,1,0]
	v_pk_fma_f32 v[2:3], v[194:195], v[226:227], v[2:3] op_sel:[0,1,0]
	s_and_b64 vcc, exec, s[34:35]
	s_cbranch_vccz .LBB0_120
	v_lshl_add_u64 v[88:89], s[24:25], 2, v[80:81]
	global_load_dwordx4 v[88:91], v[88:89], off
	s_waitcnt vmcnt(0)
	v_pk_add_f32 v[10:11], v[10:11], v[90:91]
	v_pk_add_f32 v[8:9], v[8:9], v[88:89]
	v_pk_add_f32 v[14:15], v[14:15], v[90:91]
	v_pk_add_f32 v[12:13], v[12:13], v[88:89]
	v_pk_add_f32 v[6:7], v[6:7], v[90:91]
	v_pk_add_f32 v[4:5], v[4:5], v[88:89]
	v_pk_add_f32 v[2:3], v[2:3], v[90:91]
	v_pk_add_f32 v[0:1], v[0:1], v[88:89]

.LBB0_123:
	s_mov_b32 s73, 0
	s_mov_b32 s74, 0x60000
	s_mov_b32 s75, 0
	v_mov_b64_e32 v[228:229], v[88:89]
	s_mov_b32 s72, 0xc000
	v_lshl_add_u64 v[230:231], v[88:89], 0, s[72:73]
	s_mov_b32 s72, 0x18000
	v_lshl_add_u64 v[232:233], v[88:89], 0, s[72:73]
	s_mov_b32 s72, 0x24000
	v_lshl_add_u64 v[234:235], v[88:89], 0, s[72:73]
	s_mov_b32 s72, 0x30000
	v_lshl_add_u64 v[236:237], v[88:89], 0, s[72:73]
	s_mov_b32 s72, 0x3c000
	v_lshl_add_u64 v[238:239], v[88:89], 0, s[72:73]
	s_mov_b32 s72, 0x48000
	v_lshl_add_u64 v[240:241], v[88:89], 0, s[72:73]
	s_mov_b32 s72, 0x54000
	v_lshl_add_u64 v[242:243], v[88:89], 0, s[72:73]
	global_load_dwordx4 v[164:167], v[228:229], off
	v_lshl_add_u64 v[228:229], v[228:229], 0, s[74:75]
	global_load_dwordx4 v[168:171], v[230:231], off
	v_lshl_add_u64 v[230:231], v[230:231], 0, s[74:75]
	global_load_dwordx4 v[172:175], v[232:233], off
	v_lshl_add_u64 v[232:233], v[232:233], 0, s[74:75]
	global_load_dwordx4 v[176:179], v[234:235], off
	v_lshl_add_u64 v[234:235], v[234:235], 0, s[74:75]
	global_load_dwordx4 v[180:183], v[236:237], off
	v_lshl_add_u64 v[236:237], v[236:237], 0, s[74:75]
	global_load_dwordx4 v[184:187], v[238:239], off
	v_lshl_add_u64 v[238:239], v[238:239], 0, s[74:75]
	global_load_dwordx4 v[188:191], v[240:241], off
	v_lshl_add_u64 v[240:241], v[240:241], 0, s[74:75]
	global_load_dwordx4 v[192:195], v[242:243], off
	v_lshl_add_u64 v[242:243], v[242:243], 0, s[74:75]
	s_mov_b32 s76, 31
.Lgemv_mod_loop:
	v_mov_b32_e32 v244, s4
	ds_read_b128 v[196:199], v244
	ds_read_b128 v[200:203], v244 offset:16
	ds_read_b128 v[204:207], v244 offset:1024
	ds_read_b128 v[208:211], v244 offset:1040
	ds_read_b128 v[212:215], v244 offset:2048
	ds_read_b128 v[216:219], v244 offset:2064
	ds_read_b128 v[220:223], v244 offset:3072
	ds_read_b128 v[224:227], v244 offset:3088
	s_add_i32 s4, s4, 32
	s_waitcnt lgkmcnt(0)
	s_waitcnt vmcnt(7)
	v_pk_fma_f32 v[8:9], v[164:165], v[196:197], v[8:9] op_sel_hi:[1,0,1]
	v_pk_fma_f32 v[10:11], v[166:167], v[196:197], v[10:11] op_sel_hi:[1,0,1]
	v_pk_fma_f32 v[12:13], v[164:165], v[204:205], v[12:13] op_sel_hi:[1,0,1]
	v_pk_fma_f32 v[14:15], v[166:167], v[204:205], v[14:15] op_sel_hi:[1,0,1]
	v_pk_fma_f32 v[4:5], v[164:165], v[212:213], v[4:5] op_sel_hi:[1,0,1]
	v_pk_fma_f32 v[6:7], v[166:167], v[212:213], v[6:7] op_sel_hi:[1,0,1]
	v_pk_fma_f32 v[0:1], v[164:165], v[220:221], v[0:1] op_sel_hi:[1,0,1]
	v_pk_fma_f32 v[2:3], v[166:167], v[220:221], v[2:3] op_sel_hi:[1,0,1]
	global_load_dwordx4 v[164:167], v[228:229], off
	v_lshl_add_u64 v[228:229], v[228:229], 0, s[74:75]
	s_waitcnt vmcnt(7)
	v_pk_fma_f32 v[8:9], v[168:169], v[196:197], v[8:9] op_sel:[0,1,0]
	v_pk_fma_f32 v[10:11], v[170:171], v[196:197], v[10:11] op_sel:[0,1,0]
	v_pk_fma_f32 v[12:13], v[168:169], v[204:205], v[12:13] op_sel:[0,1,0]
	v_pk_fma_f32 v[14:15], v[170:171], v[204:205], v[14:15] op_sel:[0,1,0]
	v_pk_fma_f32 v[4:5], v[168:169], v[212:213], v[4:5] op_sel:[0,1,0]
	v_pk_fma_f32 v[6:7], v[170:171], v[212:213], v[6:7] op_sel:[0,1,0]
	v_pk_fma_f32 v[0:1], v[168:169], v[220:221], v[0:1] op_sel:[0,1,0]
	v_pk_fma_f32 v[2:3], v[170:171], v[220:221], v[2:3] op_sel:[0,1,0]
	global_load_dwordx4 v[168:171], v[230:231], off
	v_lshl_add_u64 v[230:231], v[230:231], 0, s[74:75]
	s_waitcnt vmcnt(7)
	v_pk_fma_f32 v[8:9], v[172:173], v[198:199], v[8:9] op_sel_hi:[1,0,1]
	v_pk_fma_f32 v[10:11], v[174:175], v[198:199], v[10:11] op_sel_hi:[1,0,1]
	v_pk_fma_f32 v[12:13], v[172:173], v[206:207], v[12:13] op_sel_hi:[1,0,1]
	v_pk_fma_f32 v[14:15], v[174:175], v[206:207], v[14:15] op_sel_hi:[1,0,1]
	v_pk_fma_f32 v[4:5], v[172:173], v[214:215], v[4:5] op_sel_hi:[1,0,1]
	v_pk_fma_f32 v[6:7], v[174:175], v[214:215], v[6:7] op_sel_hi:[1,0,1]
	v_pk_fma_f32 v[0:1], v[172:173], v[222:223], v[0:1] op_sel_hi:[1,0,1]
	v_pk_fma_f32 v[2:3], v[174:175], v[222:223], v[2:3] op_sel_hi:[1,0,1]
	global_load_dwordx4 v[172:175], v[232:233], off
	v_lshl_add_u64 v[232:233], v[232:233], 0, s[74:75]
	s_waitcnt vmcnt(7)
	v_pk_fma_f32 v[8:9], v[176:177], v[198:199], v[8:9] op_sel:[0,1,0]
	v_pk_fma_f32 v[10:11], v[178:179], v[198:199], v[10:11] op_sel:[0,1,0]
	v_pk_fma_f32 v[12:13], v[176:177], v[206:207], v[12:13] op_sel:[0,1,0]
	v_pk_fma_f32 v[14:15], v[178:179], v[206:207], v[14:15] op_sel:[0,1,0]
	v_pk_fma_f32 v[4:5], v[176:177], v[214:215], v[4:5] op_sel:[0,1,0]
	v_pk_fma_f32 v[6:7], v[178:179], v[214:215], v[6:7] op_sel:[0,1,0]
	v_pk_fma_f32 v[0:1], v[176:177], v[222:223], v[0:1] op_sel:[0,1,0]
	v_pk_fma_f32 v[2:3], v[178:179], v[222:223], v[2:3] op_sel:[0,1,0]
	global_load_dwordx4 v[176:179], v[234:235], off
	v_lshl_add_u64 v[234:235], v[234:235], 0, s[74:75]
	s_waitcnt vmcnt(7)
	v_pk_fma_f32 v[8:9], v[180:181], v[200:201], v[8:9] op_sel_hi:[1,0,1]
	v_pk_fma_f32 v[10:11], v[182:183], v[200:201], v[10:11] op_sel_hi:[1,0,1]
	v_pk_fma_f32 v[12:13], v[180:181], v[208:209], v[12:13] op_sel_hi:[1,0,1]
	v_pk_fma_f32 v[14:15], v[182:183], v[208:209], v[14:15] op_sel_hi:[1,0,1]
	v_pk_fma_f32 v[4:5], v[180:181], v[216:217], v[4:5] op_sel_hi:[1,0,1]
	v_pk_fma_f32 v[6:7], v[182:183], v[216:217], v[6:7] op_sel_hi:[1,0,1]
	v_pk_fma_f32 v[0:1], v[180:181], v[224:225], v[0:1] op_sel_hi:[1,0,1]
	v_pk_fma_f32 v[2:3], v[182:183], v[224:225], v[2:3] op_sel_hi:[1,0,1]
	global_load_dwordx4 v[180:183], v[236:237], off
	v_lshl_add_u64 v[236:237], v[236:237], 0, s[74:75]
	s_waitcnt vmcnt(7)
	v_pk_fma_f32 v[8:9], v[184:185], v[200:201], v[8:9] op_sel:[0,1,0]
	v_pk_fma_f32 v[10:11], v[186:187], v[200:201], v[10:11] op_sel:[0,1,0]
	v_pk_fma_f32 v[12:13], v[184:185], v[208:209], v[12:13] op_sel:[0,1,0]
	v_pk_fma_f32 v[14:15], v[186:187], v[208:209], v[14:15] op_sel:[0,1,0]
	v_pk_fma_f32 v[4:5], v[184:185], v[216:217], v[4:5] op_sel:[0,1,0]
	v_pk_fma_f32 v[6:7], v[186:187], v[216:217], v[6:7] op_sel:[0,1,0]
	v_pk_fma_f32 v[0:1], v[184:185], v[224:225], v[0:1] op_sel:[0,1,0]
	v_pk_fma_f32 v[2:3], v[186:187], v[224:225], v[2:3] op_sel:[0,1,0]
	global_load_dwordx4 v[184:187], v[238:239], off
	v_lshl_add_u64 v[238:239], v[238:239], 0, s[74:75]
	s_waitcnt vmcnt(7)
	v_pk_fma_f32 v[8:9], v[188:189], v[202:203], v[8:9] op_sel_hi:[1,0,1]
	v_pk_fma_f32 v[10:11], v[190:191], v[202:203], v[10:11] op_sel_hi:[1,0,1]
	v_pk_fma_f32 v[12:13], v[188:189], v[210:211], v[12:13] op_sel_hi:[1,0,1]
	v_pk_fma_f32 v[14:15], v[190:191], v[210:211], v[14:15] op_sel_hi:[1,0,1]
	v_pk_fma_f32 v[4:5], v[188:189], v[218:219], v[4:5] op_sel_hi:[1,0,1]
	v_pk_fma_f32 v[6:7], v[190:191], v[218:219], v[6:7] op_sel_hi:[1,0,1]
	v_pk_fma_f32 v[0:1], v[188:189], v[226:227], v[0:1] op_sel_hi:[1,0,1]
	v_pk_fma_f32 v[2:3], v[190:191], v[226:227], v[2:3] op_sel_hi:[1,0,1]
	global_load_dwordx4 v[188:191], v[240:241], off
	v_lshl_add_u64 v[240:241], v[240:241], 0, s[74:75]
	s_waitcnt vmcnt(7)
	v_pk_fma_f32 v[8:9], v[192:193], v[202:203], v[8:9] op_sel:[0,1,0]
	v_pk_fma_f32 v[10:11], v[194:195], v[202:203], v[10:11] op_sel:[0,1,0]
	v_pk_fma_f32 v[12:13], v[192:193], v[210:211], v[12:13] op_sel:[0,1,0]
	v_pk_fma_f32 v[14:15], v[194:195], v[210:211], v[14:15] op_sel:[0,1,0]
	v_pk_fma_f32 v[4:5], v[192:193], v[218:219], v[4:5] op_sel:[0,1,0]
	v_pk_fma_f32 v[6:7], v[194:195], v[218:219], v[6:7] op_sel:[0,1,0]
	v_pk_fma_f32 v[0:1], v[192:193], v[226:227], v[0:1] op_sel:[0,1,0]
	v_pk_fma_f32 v[2:3], v[194:195], v[226:227], v[2:3] op_sel:[0,1,0]
	global_load_dwordx4 v[192:195], v[242:243], off
	v_lshl_add_u64 v[242:243], v[242:243], 0, s[74:75]
	s_add_i32 s76, s76, -1
	s_cmp_eq_u32 s76, 0
	s_cbranch_scc0 .Lgemv_mod_loop
	v_mov_b32_e32 v244, s4
	ds_read_b128 v[196:199], v244
	ds_read_b128 v[200:203], v244 offset:16
	ds_read_b128 v[204:207], v244 offset:1024
	ds_read_b128 v[208:211], v244 offset:1040
	ds_read_b128 v[212:215], v244 offset:2048
	ds_read_b128 v[216:219], v244 offset:2064
	ds_read_b128 v[220:223], v244 offset:3072
	ds_read_b128 v[224:227], v244 offset:3088
	s_waitcnt lgkmcnt(0)
	s_waitcnt vmcnt(7)
	v_pk_fma_f32 v[8:9], v[164:165], v[196:197], v[8:9] op_sel_hi:[1,0,1]
	v_pk_fma_f32 v[10:11], v[166:167], v[196:197], v[10:11] op_sel_hi:[1,0,1]
	v_pk_fma_f32 v[12:13], v[164:165], v[204:205], v[12:13] op_sel_hi:[1,0,1]
	v_pk_fma_f32 v[14:15], v[166:167], v[204:205], v[14:15] op_sel_hi:[1,0,1]
	v_pk_fma_f32 v[4:5], v[164:165], v[212:213], v[4:5] op_sel_hi:[1,0,1]
	v_pk_fma_f32 v[6:7], v[166:167], v[212:213], v[6:7] op_sel_hi:[1,0,1]
	v_pk_fma_f32 v[0:1], v[164:165], v[220:221], v[0:1] op_sel_hi:[1,0,1]
	v_pk_fma_f32 v[2:3], v[166:167], v[220:221], v[2:3] op_sel_hi:[1,0,1]
	s_waitcnt vmcnt(6)
	v_pk_fma_f32 v[8:9], v[168:169], v[196:197], v[8:9] op_sel:[0,1,0]
	v_pk_fma_f32 v[10:11], v[170:171], v[196:197], v[10:11] op_sel:[0,1,0]
	v_pk_fma_f32 v[12:13], v[168:169], v[204:205], v[12:13] op_sel:[0,1,0]
	v_pk_fma_f32 v[14:15], v[170:171], v[204:205], v[14:15] op_sel:[0,1,0]
	v_pk_fma_f32 v[4:5], v[168:169], v[212:213], v[4:5] op_sel:[0,1,0]
	v_pk_fma_f32 v[6:7], v[170:171], v[212:213], v[6:7] op_sel:[0,1,0]
	v_pk_fma_f32 v[0:1], v[168:169], v[220:221], v[0:1] op_sel:[0,1,0]
	v_pk_fma_f32 v[2:3], v[170:171], v[220:221], v[2:3] op_sel:[0,1,0]
	s_waitcnt vmcnt(5)
	v_pk_fma_f32 v[8:9], v[172:173], v[198:199], v[8:9] op_sel_hi:[1,0,1]
	v_pk_fma_f32 v[10:11], v[174:175], v[198:199], v[10:11] op_sel_hi:[1,0,1]
	v_pk_fma_f32 v[12:13], v[172:173], v[206:207], v[12:13] op_sel_hi:[1,0,1]
	v_pk_fma_f32 v[14:15], v[174:175], v[206:207], v[14:15] op_sel_hi:[1,0,1]
	v_pk_fma_f32 v[4:5], v[172:173], v[214:215], v[4:5] op_sel_hi:[1,0,1]
	v_pk_fma_f32 v[6:7], v[174:175], v[214:215], v[6:7] op_sel_hi:[1,0,1]
	v_pk_fma_f32 v[0:1], v[172:173], v[222:223], v[0:1] op_sel_hi:[1,0,1]
	v_pk_fma_f32 v[2:3], v[174:175], v[222:223], v[2:3] op_sel_hi:[1,0,1]
	s_waitcnt vmcnt(4)
	v_pk_fma_f32 v[8:9], v[176:177], v[198:199], v[8:9] op_sel:[0,1,0]
	v_pk_fma_f32 v[10:11], v[178:179], v[198:199], v[10:11] op_sel:[0,1,0]
	v_pk_fma_f32 v[12:13], v[176:177], v[206:207], v[12:13] op_sel:[0,1,0]
	v_pk_fma_f32 v[14:15], v[178:179], v[206:207], v[14:15] op_sel:[0,1,0]
	v_pk_fma_f32 v[4:5], v[176:177], v[214:215], v[4:5] op_sel:[0,1,0]
	v_pk_fma_f32 v[6:7], v[178:179], v[214:215], v[6:7] op_sel:[0,1,0]
	v_pk_fma_f32 v[0:1], v[176:177], v[222:223], v[0:1] op_sel:[0,1,0]
	v_pk_fma_f32 v[2:3], v[178:179], v[222:223], v[2:3] op_sel:[0,1,0]
	s_waitcnt vmcnt(3)
	v_pk_fma_f32 v[8:9], v[180:181], v[200:201], v[8:9] op_sel_hi:[1,0,1]
	v_pk_fma_f32 v[10:11], v[182:183], v[200:201], v[10:11] op_sel_hi:[1,0,1]
	v_pk_fma_f32 v[12:13], v[180:181], v[208:209], v[12:13] op_sel_hi:[1,0,1]
	v_pk_fma_f32 v[14:15], v[182:183], v[208:209], v[14:15] op_sel_hi:[1,0,1]
	v_pk_fma_f32 v[4:5], v[180:181], v[216:217], v[4:5] op_sel_hi:[1,0,1]
	v_pk_fma_f32 v[6:7], v[182:183], v[216:217], v[6:7] op_sel_hi:[1,0,1]
	v_pk_fma_f32 v[0:1], v[180:181], v[224:225], v[0:1] op_sel_hi:[1,0,1]
	v_pk_fma_f32 v[2:3], v[182:183], v[224:225], v[2:3] op_sel_hi:[1,0,1]
	s_waitcnt vmcnt(2)
	v_pk_fma_f32 v[8:9], v[184:185], v[200:201], v[8:9] op_sel:[0,1,0]
	v_pk_fma_f32 v[10:11], v[186:187], v[200:201], v[10:11] op_sel:[0,1,0]
	v_pk_fma_f32 v[12:13], v[184:185], v[208:209], v[12:13] op_sel:[0,1,0]
	v_pk_fma_f32 v[14:15], v[186:187], v[208:209], v[14:15] op_sel:[0,1,0]
	v_pk_fma_f32 v[4:5], v[184:185], v[216:217], v[4:5] op_sel:[0,1,0]
	v_pk_fma_f32 v[6:7], v[186:187], v[216:217], v[6:7] op_sel:[0,1,0]
	v_pk_fma_f32 v[0:1], v[184:185], v[224:225], v[0:1] op_sel:[0,1,0]
	v_pk_fma_f32 v[2:3], v[186:187], v[224:225], v[2:3] op_sel:[0,1,0]
	s_waitcnt vmcnt(1)
	v_pk_fma_f32 v[8:9], v[188:189], v[202:203], v[8:9] op_sel_hi:[1,0,1]
	v_pk_fma_f32 v[10:11], v[190:191], v[202:203], v[10:11] op_sel_hi:[1,0,1]
	v_pk_fma_f32 v[12:13], v[188:189], v[210:211], v[12:13] op_sel_hi:[1,0,1]
	v_pk_fma_f32 v[14:15], v[190:191], v[210:211], v[14:15] op_sel_hi:[1,0,1]
	v_pk_fma_f32 v[4:5], v[188:189], v[218:219], v[4:5] op_sel_hi:[1,0,1]
	v_pk_fma_f32 v[6:7], v[190:191], v[218:219], v[6:7] op_sel_hi:[1,0,1]
	v_pk_fma_f32 v[0:1], v[188:189], v[226:227], v[0:1] op_sel_hi:[1,0,1]
	v_pk_fma_f32 v[2:3], v[190:191], v[226:227], v[2:3] op_sel_hi:[1,0,1]
	s_waitcnt vmcnt(0)
	v_pk_fma_f32 v[8:9], v[192:193], v[202:203], v[8:9] op_sel:[0,1,0]
	v_pk_fma_f32 v[10:11], v[194:195], v[202:203], v[10:11] op_sel:[0,1,0]
	v_pk_fma_f32 v[12:13], v[192:193], v[210:211], v[12:13] op_sel:[0,1,0]
	v_pk_fma_f32 v[14:15], v[194:195], v[210:211], v[14:15] op_sel:[0,1,0]
	v_pk_fma_f32 v[4:5], v[192:193], v[218:219], v[4:5] op_sel:[0,1,0]
	v_pk_fma_f32 v[6:7], v[194:195], v[218:219], v[6:7] op_sel:[0,1,0]
	v_pk_fma_f32 v[0:1], v[192:193], v[226:227], v[0:1] op_sel:[0,1,0]
	v_pk_fma_f32 v[2:3], v[194:195], v[226:227], v[2:3] op_sel:[0,1,0]
	s_and_b64 vcc, exec, s[34:35]
	s_cbranch_vccz .LBB0_8
	s_mul_i32 s2, s24, 0x3000
	s_ashr_i32 s3, s2, 31
	v_readlane_b32 s4, v250, 6
	s_lshl_b64 s[2:3], s[2:3], 2
	v_readlane_b32 s12, v250, 14
	v_readlane_b32 s13, v250, 15
	s_add_u32 s2, s12, s2
	s_addc_u32 s3, s13, s3
	s_add_u32 s2, s2, s0
	s_addc_u32 s3, s3, s1
	global_load_dwordx4 v[88:91], v18, s[2:3]
	v_readlane_b32 s5, v250, 7
	v_readlane_b32 s6, v250, 8
	v_readlane_b32 s7, v250, 9
	v_readlane_b32 s8, v250, 10
	v_readlane_b32 s9, v250, 11
	v_readlane_b32 s10, v250, 12
	v_readlane_b32 s11, v250, 13
	v_readlane_b32 s14, v250, 16
	v_readlane_b32 s15, v250, 17
	v_readlane_b32 s16, v250, 18
	v_readlane_b32 s17, v250, 19
	v_readlane_b32 s18, v250, 20
	v_readlane_b32 s19, v250, 21
	s_waitcnt vmcnt(0)
	v_pk_add_f32 v[10:11], v[10:11], v[90:91]
	v_pk_add_f32 v[8:9], v[8:9], v[88:89]
	v_pk_add_f32 v[14:15], v[14:15], v[90:91]
	v_pk_add_f32 v[12:13], v[12:13], v[88:89]
	v_pk_add_f32 v[6:7], v[6:7], v[90:91]
	v_pk_add_f32 v[4:5], v[4:5], v[88:89]
	v_pk_add_f32 v[2:3], v[2:3], v[90:91]
	v_pk_add_f32 v[0:1], v[0:1], v[88:89]
	s_branch .LBB0_8
